# as v31 plus even-conv token loop: rope-table load issued early, per-token wait counted (no store drain)
# speedup vs baseline: 1.0018x; 1.0018x over previous
; __global__ void __launch_bounds__(NTHREADS) mk_fwd(Params P) {
;     ...
;                         for (int m = t0; m < t1; ++m) {
;                             const int S = m < TP ? 8192 : 4096, pos = m & (S - 1);
;                             bf16_t* zr = Z + (size_t)m * ZLD;
;                             const u32x4 cbg = rbg, cql = rql, ckl = rkl, ccn = rcn, cxn = rxn; const unsigned krw = rkr;
;                             if (m + 1 < t1) EV_PREFETCH(m + 1);
;     ...
; #pragma unroll
;                             for (int j = 0; j < 8; ++j) { gp[j] = gc[j]; gc[j] = gn[j]; }
;                         }
.LBB0_1641:
	s_or_b64 exec, exec, s[50:51]
	v_mov_b32_e32 v88, v53
	v_mov_b32_e32 v96, v55
	s_add_u32 s2, s2, 0x1600
	s_waitcnt vmcnt(4)
	v_mov_b64_e32 v[54:55], v[30:31]
	v_mov_b64_e32 v[50:51], v[26:27]
	v_mov_b64_e32 v[38:39], v[34:35]
	v_mov_b32_e32 v98, v57
	v_mov_b32_e32 v100, v59
	s_addc_u32 s3, s3, 0
	v_lshl_add_u64 v[72:73], v[72:73], 0, 64
	s_andn2_b64 vcc, exec, s[52:53]
	v_mov_b64_e32 v[52:53], v[28:29]
	v_mov_b64_e32 v[48:49], v[24:25]
	v_mov_b64_e32 v[36:37], v[32:33]
	v_mov_b32_e32 v102, v103
	s_mov_b32 s50, s25
	v_mov_b64_e32 v[94:95], v[86:87]
	v_mov_b64_e32 v[92:93], v[84:85]
	v_mov_b64_e32 v[90:91], v[82:83]
	v_mov_b64_e32 v[76:77], v[78:79]
	v_mov_b32_e32 v60, v44
	v_mov_b32_e32 v61, v45
	v_mov_b32_e32 v62, v46
	v_mov_b32_e32 v63, v47
	v_mov_b32_e32 v56, v40
	v_mov_b32_e32 v57, v41
	v_mov_b32_e32 v58, v42
	v_mov_b32_e32 v59, v43
	s_cbranch_vccz .LBB0_1651

; __global__ void __launch_bounds__(NTHREADS) mk_fwd(Params P) {
;     ...
;                         for (int m = t0; m < t1; ++m) {
;                             const int S = m < TP ? 8192 : 4096, pos = m & (S - 1);
;                             bf16_t* zr = Z + (size_t)m * ZLD;
;                             const u32x4 cbg = rbg, cql = rql, ckl = rkl, ccn = rcn, cxn = rxn; const unsigned krw = rkr;
;                             if (m + 1 < t1) EV_PREFETCH(m + 1);
;                             float bg[8], gn[8], acc8[8];
;                             unpack8(cbg, bg); unpack8(ccn, ta); unpack8(cxn, tb);
; #pragma unroll
;                             for (int j = 0; j < 8; ++j) gn[j] = ta[j] * tb[j];
;                             const float fp = pos > 0 ? 1.f : 0.f, fn = pos < S - 1 ? 1.f : 0.f;
; #pragma unroll
;                             for (int j = 0; j < 8; ++j) acc8[j] = bg[j] * (w1[j] * gc[j] + fp * w0[j] * gp[j] + fn * w2[j] * gn[j]);
;                             float ql[8], kl[8]; float sq = 0.f, sk = 0.f;
;                             unpack8(cql, ql); unpack8(ckl, kl);
; #pragma unroll
;                             for (int j = 0; j < 8; ++j) { sq += ql[j] * ql[j]; sk += kl[j] * kl[j]; }
;                             if (lane >= 48) sq = 0.f;
;                             if (lane >= 32) sk = 0.f;
;                             sq = wave_sum(sq); sk = wave_sum(sk);
;                             const float rq = rsqrtf(sq * (1.f / 384.f) + EPS), rk = rsqrtf(sk * (1.f / 256.f) + EPS);
;                             *(u32x4*)(zr + lane * 8) = pack8(acc8);
;                             if (lane < 48) {
; #pragma unroll
;                                 for (int j = 0; j < 8; ++j) ql[j] *= rq;
;                                 *(u32x4*)(zr + 1536 + lane * 8) = pack8(ql); }
;                             if (lane < 32) {
; #pragma unroll
;                                 for (int j = 0; j < 8; ++j) kl[j] *= rk;
;                                 *(u32x4*)(zr + 1920 + lane * 8) = pack8(kl); }
;                             if (lane < 16) { const float x1 = bf_lo(krw), x2 = bf_hi(krw); const f32x2 cs = *(const f32x2*)(rope_tab + ((size_t)pos * 16 + lane) * 2);
;                                 *(unsigned*)(KPE + (size_t)m * 32 + lane * 2) = cvt_pk_bf16(x1 * cs.x - x2 * cs.y, x1 * cs.y + x2 * cs.x); }
.LBB0_1645:
	s_cmpk_lt_i32 s50, 0x4000
	s_movk_i32 s0, 0x1fff
	s_cselect_b32 s12, s0, 0xfff
	s_and_b32 s26, s12, s50
	v_lshl_or_b32 v124, s26, 7, v80
	global_load_dwordx2 v[122:123], v124, s[78:79]
	s_cmp_eq_u32 s26, 0
	s_cselect_b64 s[0:1], -1, 0
	s_cmp_eq_u32 s26, s12
	v_cndmask_b32_e64 v121, 1.0, 0, s[0:1]
	s_cselect_b64 s[0:1], -1, 0
	v_lshlrev_b32_e32 v88, 16, v52
	v_and_b32_e32 v96, 0xffff0000, v52
	v_lshlrev_b32_e32 v98, 16, v53
	v_and_b32_e32 v100, 0xffff0000, v53
	v_lshlrev_b32_e32 v53, 16, v60
	v_lshlrev_b32_e32 v99, 16, v62
	v_and_b32_e32 v101, 0xffff0000, v62
	v_lshlrev_b32_e32 v105, 16, v63
	v_and_b32_e32 v107, 0xffff0000, v63
	v_lshlrev_b32_e32 v63, 16, v56
	v_cndmask_b32_e64 v119, 1.0, 0, s[0:1]
	v_mul_f32_e32 v52, v121, v4
	v_mov_b32_e32 v62, v94
	v_mov_b32_e32 v118, v86
	v_lshlrev_b32_e32 v111, 16, v58
	v_and_b32_e32 v113, 0xffff0000, v58
	v_lshlrev_b32_e32 v115, 16, v59
	v_and_b32_e32 v117, 0xffff0000, v59
	v_pk_mul_f32 v[52:53], v[52:53], v[62:63]
	v_pk_mul_f32 v[58:59], v[12:13], v[118:119]
	v_lshlrev_b32_e32 v104, 16, v54
	v_add_f32_e32 v52, v58, v52
	v_fmac_f32_e32 v52, v59, v53
	v_and_b32_e32 v106, 0xffff0000, v54
	v_lshlrev_b32_e32 v116, 16, v55
	v_and_b32_e32 v120, 0xffff0000, v55
	v_and_b32_e32 v55, 0xffff0000, v60
	v_and_b32_e32 v89, 0xffff0000, v56
	v_mul_f32_e32 v94, v52, v88
	v_mul_f32_e32 v54, v121, v5
	v_mov_b32_e32 v88, v95
	v_mov_b32_e32 v118, v87
	v_pk_mul_f32 v[88:89], v[54:55], v[88:89]
	v_pk_mul_f32 v[54:55], v[16:17], v[118:119]
	v_lshlrev_b32_e32 v97, 16, v61
	v_add_f32_e32 v52, v54, v88
	v_fmac_f32_e32 v52, v55, v89
	v_lshlrev_b32_e32 v109, 16, v57
	v_mul_f32_e32 v95, v52, v96
	v_mul_f32_e32 v96, v121, v6
	v_mov_b32_e32 v108, v92
	v_mov_b32_e32 v118, v84
	v_pk_mul_f32 v[54:55], v[96:97], v[108:109]
	v_pk_mul_f32 v[58:59], v[14:15], v[118:119]
	v_and_b32_e32 v61, 0xffff0000, v61
	v_and_b32_e32 v57, 0xffff0000, v57
	v_add_f32_e32 v52, v58, v54
	v_mul_f32_e32 v60, v121, v7
	v_mov_b32_e32 v56, v93
	v_mov_b32_e32 v118, v85
	v_fmac_f32_e32 v52, v59, v55
	v_pk_mul_f32 v[96:97], v[60:61], v[56:57]
	v_pk_mul_f32 v[56:57], v[18:19], v[118:119]
	v_mul_f32_e32 v108, v52, v98
	v_add_f32_e32 v52, v56, v96
	v_mul_f32_e32 v98, v121, v0
	v_mov_b32_e32 v110, v90
	v_mov_b32_e32 v118, v82
	v_fmac_f32_e32 v52, v57, v97
	v_pk_mul_f32 v[56:57], v[98:99], v[110:111]
	v_pk_mul_f32 v[58:59], v[8:9], v[118:119]
	v_mul_f32_e32 v93, v52, v100
	v_add_f32_e32 v52, v58, v56
	v_mul_f32_e32 v100, v121, v1
	v_mov_b32_e32 v112, v91
	v_mov_b32_e32 v118, v83
	v_fmac_f32_e32 v52, v59, v57
	v_pk_mul_f32 v[98:99], v[100:101], v[112:113]
	v_pk_mul_f32 v[58:59], v[20:21], v[118:119]
	v_mul_f32_e32 v96, v52, v104
	v_add_f32_e32 v52, v58, v98
	v_mul_f32_e32 v104, v121, v2
	v_mov_b32_e32 v114, v76
	v_mov_b32_e32 v118, v78
	v_fmac_f32_e32 v52, v59, v99
	v_pk_mul_f32 v[58:59], v[104:105], v[114:115]
	v_pk_mul_f32 v[60:61], v[10:11], v[118:119]
	v_mul_f32_e32 v98, v52, v106
	v_add_f32_e32 v52, v60, v58
	v_fmac_f32_e32 v52, v61, v59
	v_and_b32_e32 v58, 0xffff0000, v48
	v_lshlrev_b32_e32 v60, 16, v49
	v_and_b32_e32 v61, 0xffff0000, v49
	v_and_b32_e32 v49, 0xffff0000, v36
	v_lshlrev_b32_e32 v56, 16, v48
	v_lshlrev_b32_e32 v62, 16, v50
	v_and_b32_e32 v63, 0xffff0000, v50
	v_lshlrev_b32_e32 v76, 16, v51
	v_and_b32_e32 v88, 0xffff0000, v51
	v_lshlrev_b32_e32 v48, 16, v36
	v_lshlrev_b32_e32 v50, 16, v37
	v_and_b32_e32 v51, 0xffff0000, v37
	v_mul_f32_e32 v36, v58, v58
	v_mul_f32_e32 v37, v49, v49
	v_fmac_f32_e32 v36, v56, v56
	v_fmac_f32_e32 v37, v48, v48
	v_fmac_f32_e32 v36, v60, v60
	v_fmac_f32_e32 v37, v50, v50
	v_mul_f32_e32 v109, v52, v116
	v_lshlrev_b32_e32 v52, 16, v38
	v_fmac_f32_e32 v36, v61, v61
	v_fmac_f32_e32 v37, v51, v51
	v_and_b32_e32 v38, 0xffff0000, v38
	v_fmac_f32_e32 v36, v62, v62
	v_fmac_f32_e32 v37, v52, v52
	v_lshlrev_b32_e32 v54, 16, v39
	v_fmac_f32_e32 v36, v63, v63
	v_fmac_f32_e32 v37, v38, v38
	v_and_b32_e32 v39, 0xffff0000, v39
	v_fmac_f32_e32 v36, v76, v76
	v_fmac_f32_e32 v37, v54, v54
	v_fmac_f32_e32 v36, v88, v88
	v_fmac_f32_e32 v37, v39, v39
	v_cndmask_b32_e64 v36, v36, 0, s[42:43]
	v_cndmask_b32_e64 v37, v37, 0, s[44:45]
	ds_swizzle_b32 v90, v36 offset:swizzle(SWAP,1)
	ds_swizzle_b32 v91, v37 offset:swizzle(SWAP,1)
	v_mov_b32_e32 v116, v77
	v_mul_f32_e32 v106, v121, v3
	v_mov_b32_e32 v118, v79
	s_waitcnt lgkmcnt(1)
	v_add_f32_e32 v36, v36, v90
	s_waitcnt lgkmcnt(0)
	v_add_f32_e32 v37, v37, v91
	ds_swizzle_b32 v90, v36 offset:swizzle(SWAP,2)
	ds_swizzle_b32 v77, v37 offset:swizzle(SWAP,2)
	v_pk_mul_f32 v[100:101], v[106:107], v[116:117]
	v_cvt_pk_bf16_f32 v104, v94, v95
	v_cvt_pk_bf16_f32 v105, v108, v93
	s_waitcnt lgkmcnt(1)
	v_add_f32_e32 v36, v36, v90
	s_waitcnt lgkmcnt(0)
	v_add_f32_e32 v77, v37, v77
	ds_swizzle_b32 v90, v36 offset:swizzle(SWAP,4)
	ds_swizzle_b32 v91, v77 offset:swizzle(SWAP,4)
	v_cvt_pk_bf16_f32 v106, v96, v98
	s_waitcnt lgkmcnt(1)
	v_add_f32_e32 v90, v36, v90
	s_waitcnt lgkmcnt(0)
	v_add_f32_e32 v77, v77, v91
	ds_swizzle_b32 v92, v90 offset:swizzle(SWAP,8)
	ds_swizzle_b32 v91, v77 offset:swizzle(SWAP,8)
	v_pk_mul_f32 v[36:37], v[22:23], v[118:119]
	s_waitcnt lgkmcnt(1)
	v_add_f32_e32 v90, v90, v92
	v_add_f32_e32 v36, v36, v100
	v_fmac_f32_e32 v36, v37, v101
	s_waitcnt lgkmcnt(0)
	v_add_f32_e32 v37, v77, v91
	ds_swizzle_b32 v92, v90 offset:swizzle(SWAP,16)
	ds_swizzle_b32 v77, v37 offset:swizzle(SWAP,16)
	v_mul_f32_e32 v36, v36, v120
	v_cvt_pk_bf16_f32 v107, v109, v36
	s_waitcnt lgkmcnt(1)
	v_add_f32_e32 v91, v90, v92
	s_waitcnt lgkmcnt(0)
	v_add_f32_e32 v77, v37, v77
	v_lshl_add_u64 v[36:37], s[2:3], 0, v[74:75]
	v_mov_b32_e32 v92, v91
	v_mov_b32_e32 v90, v77
	v_add_co_u32_e32 v94, vcc, 0xea00000, v36
	v_permlane32_swap_b32_e32 v91, v92
	v_permlane32_swap_b32_e32 v77, v90
	v_addc_co_u32_e32 v95, vcc, 0, v37, vcc
	global_store_dwordx4 v[94:95], v[104:107], off
	s_and_saveexec_b64 s[50:51], s[40:41]
	s_cbranch_execz .LBB0_1648
	v_add_f32_e32 v91, v91, v92
	v_mov_b32_e32 v92, 0x358637bd
	v_fmamk_f32 v91, v91, 0x3b2aaaab, v92
	v_mul_f32_e32 v92, 0x4b800000, v91
	v_cmp_gt_f32_e32 vcc, s10, v91
	s_nop 1
	v_cndmask_b32_e32 v91, v91, v92, vcc
	v_rsq_f32_e32 v91, v91
	s_nop 0
	v_mul_f32_e32 v92, 0x45800000, v91
	v_cndmask_b32_e32 v91, v91, v92, vcc
	v_mul_f32_e32 v92, v91, v60
	v_mul_f32_e32 v61, v91, v61
	v_mul_f32_e32 v56, v91, v56
	v_mul_f32_e32 v58, v91, v58
	v_cvt_pk_bf16_f32 v60, v56, v58
	v_cvt_pk_bf16_f32 v61, v92, v61
	v_add_co_u32_e32 v92, vcc, 0xea00000, v36
	v_mul_f32_e32 v62, v91, v62
	v_mul_f32_e32 v63, v91, v63
	v_addc_co_u32_e32 v93, vcc, 0, v37, vcc
	v_mul_f32_e32 v76, v91, v76
	v_mul_f32_e32 v88, v91, v88
	v_cvt_pk_bf16_f32 v62, v62, v63
	v_cvt_pk_bf16_f32 v63, v76, v88
	global_store_dwordx4 v[92:93], v[60:63], off offset:3072
	s_or_b64 exec, exec, s[50:51]
	s_and_saveexec_b64 s[50:51], s[46:47]
	s_cbranch_execnz .LBB0_1649

; __device__ __forceinline__ unsigned cvt_pk_bf16(float lo, float hi) { unsigned r; asm volatile("v_cvt_pk_bf16_f32 %0, %1, %2" : "=v"(r) : "v"(lo), "v"(hi)); return r; }
; __device__ __forceinline__ float bf_lo(unsigned w) { return __uint_as_float(w << 16); }
; __device__ __forceinline__ float bf_hi(unsigned w) { return __uint_as_float(w & 0xffff0000u); }
; __global__ void __launch_bounds__(NTHREADS) mk_fwd(Params P) {
;     ...
;                             if (lane < 16) { const float x1 = bf_lo(krw), x2 = bf_hi(krw); const f32x2 cs = *(const f32x2*)(rope_tab + ((size_t)pos * 16 + lane) * 2);
;                                 *(unsigned*)(KPE + (size_t)m * 32 + lane * 2) = cvt_pk_bf16(x1 * cs.x - x2 * cs.y, x1 * cs.y + x2 * cs.x); }
.LBB0_1650:
	v_lshlrev_b32_e32 v36, 16, v102
	v_and_b32_e32 v37, 0xffff0000, v102
	s_waitcnt vmcnt(3)
	v_pk_mul_f32 v[48:49], v[122:123], v[36:37]
	v_pk_mul_f32 v[36:37], v[122:123], v[36:37] op_sel:[1,0] op_sel_hi:[0,1]
	v_add_f32_e32 v36, v36, v37
	v_sub_f32_e32 v48, v48, v49
	v_cvt_pk_bf16_f32 v36, v48, v36
	global_store_dword v[72:73], v36, off
	s_branch .LBB0_1641
